# P2/P9 tile switch: leading half's epilogue-alignment barrier taken 80 instructions into its epilogue (overlaps trailing half's last MFMA block), on top of v129
# baseline (speedup 1.0000x reference)
.LBB0_125:
	ds_read_b128 v[146:149], v141
	ds_read_b128 v[150:153], v141 offset:1024
	ds_read_b128 v[154:157], v141 offset:2048
	ds_read_b128 v[158:161], v141 offset:3072
	ds_read_b128 v[162:165], v142
	ds_read_b128 v[166:169], v142 offset:1024
	ds_read_b128 v[170:173], v142 offset:2048
	ds_read_b128 v[174:177], v142 offset:3072
	s_add_u32 s68, s70, 0x100
	s_addc_u32 s69, s71, 0
	s_cmp_eq_u32 s62, 12
	s_cselect_b32 s76, s93, s68
	s_cselect_b32 s77, s29, s69
	s_cselect_b32 s74, s94, s9
	s_cselect_b32 s75, s21, s78
	s_add_u32 s72, s76, 0x80
	s_addc_u32 s73, s77, 0
	s_add_u32 s12, s70, 0x40080
	s_mov_b32 m0, s95
	s_addc_u32 s13, s71, 0
	v_mov_b32_e32 v210, v134
	ds_read_b128 v[178:181], v143
	ds_read_b128 v[182:185], v143 offset:1024
	ds_read_b128 v[186:189], v143 offset:2048
	ds_read_b128 v[190:193], v143 offset:3072
	ds_read_b128 v[194:197], v143 offset:4096
	ds_read_b128 v[198:201], v143 offset:5120
	ds_read_b128 v[202:205], v143 offset:6144
	ds_read_b128 v[206:209], v143 offset:7168
	v_mov_b32_e32 v211, v136
	global_load_lds_dwordx4 v210, s[12:13]
	s_mov_b32 m0, s96
	s_add_u32 s70, s74, 0x80
	global_load_lds_dwordx4 v211, s[12:13]
	s_waitcnt vmcnt(8)
	s_waitcnt lgkmcnt(0)
	s_addc_u32 s71, s75, 0
	s_barrier
	s_waitcnt lgkmcnt(0)
	v_mfma_f32_16x16x32_bf16 v[122:125], v[146:149], v[178:181], v[122:125]
	v_mfma_f32_16x16x32_bf16 v[114:117], v[154:157], v[178:181], v[114:117]
	v_mfma_f32_16x16x32_bf16 v[106:109], v[146:149], v[186:189], v[106:109]
	v_mfma_f32_16x16x32_bf16 v[98:101], v[154:157], v[186:189], v[98:101]
	v_mfma_f32_16x16x32_bf16 v[90:93], v[146:149], v[194:197], v[90:93]
	v_mfma_f32_16x16x32_bf16 v[82:85], v[154:157], v[194:197], v[82:85]
	v_mfma_f32_16x16x32_bf16 v[74:77], v[146:149], v[202:205], v[74:77]
	v_mfma_f32_16x16x32_bf16 v[58:61], v[154:157], v[202:205], v[58:61]
	v_mfma_f32_16x16x32_bf16 v[122:125], v[150:153], v[182:185], v[122:125]
	v_mfma_f32_16x16x32_bf16 v[114:117], v[158:161], v[182:185], v[114:117]
	v_mfma_f32_16x16x32_bf16 v[106:109], v[150:153], v[190:193], v[106:109]
	v_mfma_f32_16x16x32_bf16 v[98:101], v[158:161], v[190:193], v[98:101]
	v_mfma_f32_16x16x32_bf16 v[90:93], v[150:153], v[198:201], v[90:93]
	v_mfma_f32_16x16x32_bf16 v[82:85], v[158:161], v[198:201], v[82:85]
	v_mfma_f32_16x16x32_bf16 v[74:77], v[150:153], v[206:209], v[74:77]
	v_mfma_f32_16x16x32_bf16 v[58:61], v[158:161], v[206:209], v[58:61]
	v_mfma_f32_16x16x32_bf16 v[126:129], v[162:165], v[178:181], v[126:129]
	v_mfma_f32_16x16x32_bf16 v[118:121], v[170:173], v[178:181], v[118:121]
	v_mfma_f32_16x16x32_bf16 v[110:113], v[162:165], v[186:189], v[110:113]
	v_mfma_f32_16x16x32_bf16 v[102:105], v[170:173], v[186:189], v[102:105]
	v_mfma_f32_16x16x32_bf16 v[94:97], v[162:165], v[194:197], v[94:97]
	v_mfma_f32_16x16x32_bf16 v[86:89], v[170:173], v[194:197], v[86:89]
	v_mfma_f32_16x16x32_bf16 v[78:81], v[162:165], v[202:205], v[78:81]
	v_mfma_f32_16x16x32_bf16 v[66:69], v[170:173], v[202:205], v[66:69]
	v_mfma_f32_16x16x32_bf16 v[126:129], v[166:169], v[182:185], v[126:129]
	v_mfma_f32_16x16x32_bf16 v[118:121], v[174:177], v[182:185], v[118:121]
	v_mfma_f32_16x16x32_bf16 v[110:113], v[166:169], v[190:193], v[110:113]
	v_mfma_f32_16x16x32_bf16 v[102:105], v[174:177], v[190:193], v[102:105]
	v_mfma_f32_16x16x32_bf16 v[94:97], v[166:169], v[198:201], v[94:97]
	v_mfma_f32_16x16x32_bf16 v[86:89], v[174:177], v[198:201], v[86:89]
	v_mfma_f32_16x16x32_bf16 v[78:81], v[166:169], v[206:209], v[78:81]
	v_mfma_f32_16x16x32_bf16 v[66:69], v[174:177], v[206:209], v[66:69]
	s_barrier
	s_mov_b32 m0, s97
	s_mov_b64 s[12:13], s[74:75]
	v_mov_b32_e32 v212, v135
	ds_read_b128 v[178:181], v143 offset:16384
	ds_read_b128 v[182:185], v143 offset:17408
	ds_read_b128 v[186:189], v143 offset:18432
	ds_read_b128 v[190:193], v143 offset:19456
	ds_read_b128 v[194:197], v143 offset:20480
	ds_read_b128 v[198:201], v143 offset:21504
	ds_read_b128 v[202:205], v143 offset:22528
	ds_read_b128 v[206:209], v143 offset:23552
	v_mov_b32_e32 v213, v137
	global_load_lds_dwordx4 v212, s[12:13]
	s_mov_b32 m0, vcc_lo
	s_nop 0
	global_load_lds_dwordx4 v213, s[12:13]
	s_add_u32 s12, s74, 0x40000
	s_addc_u32 s13, s75, 0
	s_mov_b32 m0, vcc_hi
	s_nop 0
	global_load_lds_dwordx4 v212, s[12:13]
	s_mov_b32 m0, s34
	s_nop 0
	global_load_lds_dwordx4 v213, s[12:13]
	s_mov_b64 s[12:13], s[76:77]
	s_mov_b32 m0, s67
	s_nop 0
	global_load_lds_dwordx4 v210, s[12:13]
	s_mov_b32 m0, s83
	s_nop 0
	global_load_lds_dwordx4 v211, s[12:13]
	s_waitcnt vmcnt(8)
	s_waitcnt lgkmcnt(0)
	s_barrier
	s_waitcnt lgkmcnt(0)
	v_mfma_f32_16x16x32_bf16 v[62:65], v[146:149], v[178:181], v[62:65]
	v_mfma_f32_16x16x32_bf16 v[50:53], v[154:157], v[178:181], v[50:53]
	v_mfma_f32_16x16x32_bf16 v[42:45], v[146:149], v[186:189], v[42:45]
	v_mfma_f32_16x16x32_bf16 v[34:37], v[154:157], v[186:189], v[34:37]
	v_mfma_f32_16x16x32_bf16 v[26:29], v[146:149], v[194:197], v[26:29]
	v_mfma_f32_16x16x32_bf16 v[18:21], v[154:157], v[194:197], v[18:21]
	v_mfma_f32_16x16x32_bf16 v[10:13], v[146:149], v[202:205], v[10:13]
	v_mfma_f32_16x16x32_bf16 v[2:5], v[154:157], v[202:205], v[2:5]
	v_mfma_f32_16x16x32_bf16 v[62:65], v[150:153], v[182:185], v[62:65]
	v_mfma_f32_16x16x32_bf16 v[50:53], v[158:161], v[182:185], v[50:53]
	v_mfma_f32_16x16x32_bf16 v[42:45], v[150:153], v[190:193], v[42:45]
	v_mfma_f32_16x16x32_bf16 v[34:37], v[158:161], v[190:193], v[34:37]
	v_mfma_f32_16x16x32_bf16 v[26:29], v[150:153], v[198:201], v[26:29]
	v_mfma_f32_16x16x32_bf16 v[18:21], v[158:161], v[198:201], v[18:21]
	v_mfma_f32_16x16x32_bf16 v[10:13], v[150:153], v[206:209], v[10:13]
	v_mfma_f32_16x16x32_bf16 v[2:5], v[158:161], v[206:209], v[2:5]
	v_mfma_f32_16x16x32_bf16 v[70:73], v[162:165], v[178:181], v[70:73]
	v_mfma_f32_16x16x32_bf16 v[54:57], v[170:173], v[178:181], v[54:57]
	v_mfma_f32_16x16x32_bf16 v[46:49], v[162:165], v[186:189], v[46:49]
	v_mfma_f32_16x16x32_bf16 v[38:41], v[170:173], v[186:189], v[38:41]
	v_mfma_f32_16x16x32_bf16 v[30:33], v[162:165], v[194:197], v[30:33]
	v_mfma_f32_16x16x32_bf16 v[22:25], v[170:173], v[194:197], v[22:25]
	v_mfma_f32_16x16x32_bf16 v[14:17], v[162:165], v[202:205], v[14:17]
	v_mfma_f32_16x16x32_bf16 v[6:9], v[170:173], v[202:205], v[6:9]
	v_mfma_f32_16x16x32_bf16 v[70:73], v[166:169], v[182:185], v[70:73]
	v_mfma_f32_16x16x32_bf16 v[54:57], v[174:177], v[182:185], v[54:57]
	v_mfma_f32_16x16x32_bf16 v[46:49], v[166:169], v[190:193], v[46:49]
	v_mfma_f32_16x16x32_bf16 v[38:41], v[174:177], v[190:193], v[38:41]
	v_mfma_f32_16x16x32_bf16 v[30:33], v[166:169], v[198:201], v[30:33]
	v_mfma_f32_16x16x32_bf16 v[22:25], v[174:177], v[198:201], v[22:25]
	v_mfma_f32_16x16x32_bf16 v[14:17], v[166:169], v[206:209], v[14:17]
	v_mfma_f32_16x16x32_bf16 v[6:9], v[174:177], v[206:209], v[6:9]
	s_barrier
	ds_read_b128 v[146:149], v144
	ds_read_b128 v[150:153], v144 offset:1024
	ds_read_b128 v[154:157], v144 offset:2048
	ds_read_b128 v[158:161], v144 offset:3072
	ds_read_b128 v[162:165], v145
	ds_read_b128 v[166:169], v145 offset:1024
	ds_read_b128 v[170:173], v145 offset:2048
	ds_read_b128 v[174:177], v145 offset:3072
	s_add_u32 s12, s76, 0x40000
	s_addc_u32 s13, s77, 0
	s_mov_b32 m0, s84
	ds_read_b128 v[178:181], v143 offset:32768
	ds_read_b128 v[182:185], v143 offset:33792
	ds_read_b128 v[186:189], v143 offset:34816
	ds_read_b128 v[190:193], v143 offset:35840
	ds_read_b128 v[194:197], v143 offset:36864
	ds_read_b128 v[198:201], v143 offset:37888
	ds_read_b128 v[202:205], v143 offset:38912
	ds_read_b128 v[206:209], v143 offset:39936
	s_nop 0
	global_load_lds_dwordx4 v210, s[12:13]
	s_mov_b32 m0, s85
	s_nop 0
	global_load_lds_dwordx4 v211, s[12:13]
	s_waitcnt vmcnt(8)
	s_waitcnt lgkmcnt(0)
	s_barrier
	s_waitcnt lgkmcnt(0)
	v_mfma_f32_16x16x32_bf16 v[122:125], v[146:149], v[178:181], v[122:125]
	v_mfma_f32_16x16x32_bf16 v[114:117], v[154:157], v[178:181], v[114:117]
	v_mfma_f32_16x16x32_bf16 v[106:109], v[146:149], v[186:189], v[106:109]
	v_mfma_f32_16x16x32_bf16 v[98:101], v[154:157], v[186:189], v[98:101]
	v_mfma_f32_16x16x32_bf16 v[90:93], v[146:149], v[194:197], v[90:93]
	v_mfma_f32_16x16x32_bf16 v[82:85], v[154:157], v[194:197], v[82:85]
	v_mfma_f32_16x16x32_bf16 v[74:77], v[146:149], v[202:205], v[74:77]
	v_mfma_f32_16x16x32_bf16 v[58:61], v[154:157], v[202:205], v[58:61]
	v_mfma_f32_16x16x32_bf16 v[122:125], v[150:153], v[182:185], v[122:125]
	v_mfma_f32_16x16x32_bf16 v[114:117], v[158:161], v[182:185], v[114:117]
	v_mfma_f32_16x16x32_bf16 v[106:109], v[150:153], v[190:193], v[106:109]
	v_mfma_f32_16x16x32_bf16 v[98:101], v[158:161], v[190:193], v[98:101]
	v_mfma_f32_16x16x32_bf16 v[90:93], v[150:153], v[198:201], v[90:93]
	v_mfma_f32_16x16x32_bf16 v[82:85], v[158:161], v[198:201], v[82:85]
	v_mfma_f32_16x16x32_bf16 v[74:77], v[150:153], v[206:209], v[74:77]
	v_mfma_f32_16x16x32_bf16 v[58:61], v[158:161], v[206:209], v[58:61]
	v_mfma_f32_16x16x32_bf16 v[126:129], v[162:165], v[178:181], v[126:129]
	v_mfma_f32_16x16x32_bf16 v[118:121], v[170:173], v[178:181], v[118:121]
	v_mfma_f32_16x16x32_bf16 v[110:113], v[162:165], v[186:189], v[110:113]
	v_mfma_f32_16x16x32_bf16 v[102:105], v[170:173], v[186:189], v[102:105]
	v_mfma_f32_16x16x32_bf16 v[94:97], v[162:165], v[194:197], v[94:97]
	v_mfma_f32_16x16x32_bf16 v[86:89], v[170:173], v[194:197], v[86:89]
	v_mfma_f32_16x16x32_bf16 v[78:81], v[162:165], v[202:205], v[78:81]
	v_mfma_f32_16x16x32_bf16 v[66:69], v[170:173], v[202:205], v[66:69]
	v_mfma_f32_16x16x32_bf16 v[126:129], v[166:169], v[182:185], v[126:129]
	v_mfma_f32_16x16x32_bf16 v[118:121], v[174:177], v[182:185], v[118:121]
	v_mfma_f32_16x16x32_bf16 v[110:113], v[166:169], v[190:193], v[110:113]
	v_mfma_f32_16x16x32_bf16 v[102:105], v[174:177], v[190:193], v[102:105]
	v_mfma_f32_16x16x32_bf16 v[94:97], v[166:169], v[198:201], v[94:97]
	v_mfma_f32_16x16x32_bf16 v[86:89], v[174:177], v[198:201], v[86:89]
	v_mfma_f32_16x16x32_bf16 v[78:81], v[166:169], v[206:209], v[78:81]
	v_mfma_f32_16x16x32_bf16 v[66:69], v[174:177], v[206:209], v[66:69]
	s_barrier
	s_mov_b32 m0, s35
	ds_read_b128 v[178:181], v143 offset:49152
	ds_read_b128 v[182:185], v143 offset:50176
	ds_read_b128 v[186:189], v143 offset:51200
	ds_read_b128 v[190:193], v143 offset:52224
	ds_read_b128 v[194:197], v143 offset:53248
	ds_read_b128 v[198:201], v143 offset:54272
	ds_read_b128 v[202:205], v143 offset:55296
	ds_read_b128 v[206:209], v143 offset:56320
	s_add_u32 s12, s74, 0x40080
	global_load_lds_dwordx4 v212, s[70:71]
	s_mov_b32 m0, s11
	s_addc_u32 s13, s75, 0
	global_load_lds_dwordx4 v213, s[70:71]
	s_mov_b32 m0, s80
	s_nop 0
	global_load_lds_dwordx4 v212, s[12:13]
	s_mov_b32 m0, s8
	s_nop 0
	global_load_lds_dwordx4 v213, s[12:13]
	s_mov_b32 m0, s87
	s_nop 0
	global_load_lds_dwordx4 v210, s[72:73]
	s_mov_b32 m0, s88
	s_nop 0
	global_load_lds_dwordx4 v211, s[72:73]
	s_waitcnt vmcnt(8)
	s_waitcnt lgkmcnt(0)
	s_barrier
	s_waitcnt lgkmcnt(0)
	v_mfma_f32_16x16x32_bf16 v[62:65], v[146:149], v[178:181], v[62:65]
	v_mfma_f32_16x16x32_bf16 v[50:53], v[154:157], v[178:181], v[50:53]
	v_mfma_f32_16x16x32_bf16 v[42:45], v[146:149], v[186:189], v[42:45]
	v_mfma_f32_16x16x32_bf16 v[34:37], v[154:157], v[186:189], v[34:37]
	v_mfma_f32_16x16x32_bf16 v[26:29], v[146:149], v[194:197], v[26:29]
	v_mfma_f32_16x16x32_bf16 v[18:21], v[154:157], v[194:197], v[18:21]
	v_mfma_f32_16x16x32_bf16 v[10:13], v[146:149], v[202:205], v[10:13]
	v_mfma_f32_16x16x32_bf16 v[2:5], v[154:157], v[202:205], v[2:5]
	v_mfma_f32_16x16x32_bf16 v[62:65], v[150:153], v[182:185], v[62:65]
	v_mfma_f32_16x16x32_bf16 v[50:53], v[158:161], v[182:185], v[50:53]
	v_mfma_f32_16x16x32_bf16 v[42:45], v[150:153], v[190:193], v[42:45]
	v_mfma_f32_16x16x32_bf16 v[34:37], v[158:161], v[190:193], v[34:37]
	v_mfma_f32_16x16x32_bf16 v[26:29], v[150:153], v[198:201], v[26:29]
	v_mfma_f32_16x16x32_bf16 v[18:21], v[158:161], v[198:201], v[18:21]
	v_mfma_f32_16x16x32_bf16 v[10:13], v[150:153], v[206:209], v[10:13]
	v_mfma_f32_16x16x32_bf16 v[2:5], v[158:161], v[206:209], v[2:5]
	v_mfma_f32_16x16x32_bf16 v[70:73], v[162:165], v[178:181], v[70:73]
	v_mfma_f32_16x16x32_bf16 v[54:57], v[170:173], v[178:181], v[54:57]
	v_mfma_f32_16x16x32_bf16 v[46:49], v[162:165], v[186:189], v[46:49]
	v_mfma_f32_16x16x32_bf16 v[38:41], v[170:173], v[186:189], v[38:41]
	v_mfma_f32_16x16x32_bf16 v[30:33], v[162:165], v[194:197], v[30:33]
	v_mfma_f32_16x16x32_bf16 v[22:25], v[170:173], v[194:197], v[22:25]
	v_mfma_f32_16x16x32_bf16 v[14:17], v[162:165], v[202:205], v[14:17]
	v_mfma_f32_16x16x32_bf16 v[6:9], v[170:173], v[202:205], v[6:9]
	v_mfma_f32_16x16x32_bf16 v[70:73], v[166:169], v[182:185], v[70:73]
	v_mfma_f32_16x16x32_bf16 v[54:57], v[174:177], v[182:185], v[54:57]
	v_mfma_f32_16x16x32_bf16 v[46:49], v[166:169], v[190:193], v[46:49]
	v_mfma_f32_16x16x32_bf16 v[38:41], v[174:177], v[190:193], v[38:41]
	v_mfma_f32_16x16x32_bf16 v[30:33], v[166:169], v[198:201], v[30:33]
	v_mfma_f32_16x16x32_bf16 v[22:25], v[174:177], v[198:201], v[22:25]
	v_mfma_f32_16x16x32_bf16 v[14:17], v[166:169], v[206:209], v[14:17]
	v_mfma_f32_16x16x32_bf16 v[6:9], v[174:177], v[206:209], v[6:9]
	s_barrier
	s_add_i32 s62, s62, 2
	s_add_u32 s9, s9, 0x100
	s_addc_u32 s78, s78, 0
	s_cmp_gt_u32 s62, 13
	s_mov_b64 s[70:71], s[68:69]
	s_cbranch_scc0 .LBB0_125
	s_and_b64 vcc, exec, s[14:15]
	s_cbranch_vccz .LBB0_128
	s_nop 0
.LBB0_128:
	v_pk_mul_f32 v[146:147], v[122:123], s[18:19] op_sel_hi:[1,0]
	v_pk_mul_f32 v[148:149], v[124:125], s[18:19] op_sel_hi:[1,0]
	v_pk_mul_f32 v[124:125], v[124:125], v[128:129]
	v_pk_mul_f32 v[122:123], v[122:123], v[126:127]
	v_pk_mul_f32 v[126:127], v[114:115], s[18:19] op_sel_hi:[1,0]
	v_pk_mul_f32 v[128:129], v[116:117], s[18:19] op_sel_hi:[1,0]
	v_exp_f32_e32 v146, v146
	v_exp_f32_e32 v147, v147
	v_exp_f32_e32 v148, v148
	v_exp_f32_e32 v149, v149
	v_exp_f32_e32 v126, v126
	v_exp_f32_e32 v127, v127
	v_exp_f32_e32 v128, v128
	v_exp_f32_e32 v129, v129
	v_pk_add_f32 v[146:147], v[146:147], 1.0 op_sel_hi:[1,0]
	v_pk_add_f32 v[148:149], v[148:149], 1.0 op_sel_hi:[1,0]
	v_pk_add_f32 v[126:127], v[126:127], 1.0 op_sel_hi:[1,0]
	v_pk_add_f32 v[128:129], v[128:129], 1.0 op_sel_hi:[1,0]
	v_rcp_f32_e32 v146, v146
	v_rcp_f32_e32 v147, v147
	v_rcp_f32_e32 v148, v148
	v_rcp_f32_e32 v149, v149
	v_rcp_f32_e32 v126, v126
	v_rcp_f32_e32 v127, v127
	v_rcp_f32_e32 v128, v128
	v_rcp_f32_e32 v129, v129
	v_lshl_add_u32 v144, s66, 8, v138
	s_movk_i32 s8, 0xb00
	v_lshl_or_b32 v145, s92, 7, v140
	v_mul_lo_u32 v144, v144, s8
	v_pk_mul_f32 v[116:117], v[116:117], v[120:121]
	v_pk_mul_f32 v[114:115], v[114:115], v[118:119]
	v_add_lshl_u32 v144, v144, v145, 1
	v_pk_mul_f32 v[122:123], v[146:147], v[122:123]
	v_pk_mul_f32 v[124:125], v[148:149], v[124:125]
	v_pk_mul_f32 v[118:119], v[126:127], v[114:115]
	v_pk_mul_f32 v[120:121], v[128:129], v[116:117]
	v_cvt_pk_bf16_f32 v114, v122, v123
	v_cvt_pk_bf16_f32 v115, v124, v125
	v_cvt_pk_bf16_f32 v116, v118, v119
	v_add_u32_e32 v118, 0x16000, v144
	v_cvt_pk_bf16_f32 v117, v120, v121
	buffer_store_dwordx4 v[114:117], v144, s[4:7], 0 offen sc1
	s_andn2_b64 vcc, exec, s[2:3]
	s_mov_b64 s[2:3], -1
	v_pk_mul_f32 v[114:115], v[106:107], s[18:19] op_sel_hi:[1,0]
	v_pk_mul_f32 v[116:117], v[108:109], s[18:19] op_sel_hi:[1,0]
	v_pk_mul_f32 v[108:109], v[108:109], v[112:113]
	v_pk_mul_f32 v[106:107], v[106:107], v[110:111]
	v_pk_mul_f32 v[110:111], v[98:99], s[18:19] op_sel_hi:[1,0]
	v_pk_mul_f32 v[112:113], v[100:101], s[18:19] op_sel_hi:[1,0]
	v_exp_f32_e32 v114, v114
	v_exp_f32_e32 v115, v115
	v_exp_f32_e32 v116, v116
	v_exp_f32_e32 v117, v117
	v_exp_f32_e32 v110, v110
	v_exp_f32_e32 v111, v111
	v_exp_f32_e32 v112, v112
	v_exp_f32_e32 v113, v113
	v_pk_add_f32 v[114:115], v[114:115], 1.0 op_sel_hi:[1,0]
	v_pk_add_f32 v[116:117], v[116:117], 1.0 op_sel_hi:[1,0]
	v_pk_add_f32 v[110:111], v[110:111], 1.0 op_sel_hi:[1,0]
	v_pk_add_f32 v[112:113], v[112:113], 1.0 op_sel_hi:[1,0]
	v_rcp_f32_e32 v114, v114
	v_rcp_f32_e32 v115, v115
	v_rcp_f32_e32 v116, v116
	v_rcp_f32_e32 v117, v117
	v_rcp_f32_e32 v110, v110
	v_rcp_f32_e32 v111, v111
	v_rcp_f32_e32 v112, v112
	v_rcp_f32_e32 v113, v113
	v_pk_mul_f32 v[100:101], v[100:101], v[104:105]
	v_pk_mul_f32 v[98:99], v[98:99], v[102:103]
	v_pk_mul_f32 v[106:107], v[114:115], v[106:107]
	v_pk_mul_f32 v[108:109], v[116:117], v[108:109]
	v_pk_mul_f32 v[102:103], v[110:111], v[98:99]
	v_pk_mul_f32 v[104:105], v[112:113], v[100:101]
	v_cvt_pk_bf16_f32 v98, v106, v107
	v_cvt_pk_bf16_f32 v99, v108, v109
	v_cvt_pk_bf16_f32 v100, v102, v103
	s_cmp_eq_u64 s[14:15], 0
	s_cbranch_scc1 .Lmy_ab_p2
	s_barrier
.Lmy_ab_p2:
	v_add_u32_e32 v102, 0x2c000, v144
	v_cvt_pk_bf16_f32 v101, v104, v105
	buffer_store_dwordx4 v[98:101], v118, s[4:7], 0 offen sc1
	s_nop 1
	v_pk_mul_f32 v[98:99], v[90:91], s[18:19] op_sel_hi:[1,0]
	v_pk_mul_f32 v[100:101], v[92:93], s[18:19] op_sel_hi:[1,0]
	v_pk_mul_f32 v[92:93], v[92:93], v[96:97]
	v_pk_mul_f32 v[90:91], v[90:91], v[94:95]
	v_pk_mul_f32 v[94:95], v[82:83], s[18:19] op_sel_hi:[1,0]
	v_pk_mul_f32 v[96:97], v[84:85], s[18:19] op_sel_hi:[1,0]
	v_exp_f32_e32 v98, v98
	v_exp_f32_e32 v99, v99
	v_exp_f32_e32 v100, v100
	v_exp_f32_e32 v101, v101
	v_exp_f32_e32 v94, v94
	v_exp_f32_e32 v95, v95
	v_exp_f32_e32 v96, v96
	v_exp_f32_e32 v97, v97
	v_pk_add_f32 v[98:99], v[98:99], 1.0 op_sel_hi:[1,0]
	v_pk_add_f32 v[100:101], v[100:101], 1.0 op_sel_hi:[1,0]
	v_pk_add_f32 v[94:95], v[94:95], 1.0 op_sel_hi:[1,0]
	v_pk_add_f32 v[96:97], v[96:97], 1.0 op_sel_hi:[1,0]
	v_rcp_f32_e32 v98, v98
	v_rcp_f32_e32 v99, v99
	v_rcp_f32_e32 v100, v100
	v_rcp_f32_e32 v101, v101
	v_rcp_f32_e32 v94, v94
	v_rcp_f32_e32 v95, v95
	v_rcp_f32_e32 v96, v96
	v_rcp_f32_e32 v97, v97
	v_pk_mul_f32 v[84:85], v[84:85], v[88:89]
	v_pk_mul_f32 v[82:83], v[82:83], v[86:87]
	v_pk_mul_f32 v[90:91], v[98:99], v[90:91]
	v_pk_mul_f32 v[92:93], v[100:101], v[92:93]
	v_pk_mul_f32 v[86:87], v[94:95], v[82:83]
	v_pk_mul_f32 v[88:89], v[96:97], v[84:85]
	v_cvt_pk_bf16_f32 v82, v90, v91
	v_cvt_pk_bf16_f32 v83, v92, v93
	v_cvt_pk_bf16_f32 v84, v86, v87
	v_add_u32_e32 v86, 0x42000, v144
	v_cvt_pk_bf16_f32 v85, v88, v89
	buffer_store_dwordx4 v[82:85], v102, s[4:7], 0 offen sc1
	s_nop 1
	v_pk_mul_f32 v[82:83], v[74:75], s[18:19] op_sel_hi:[1,0]
	v_pk_mul_f32 v[84:85], v[76:77], s[18:19] op_sel_hi:[1,0]
	v_pk_mul_f32 v[76:77], v[76:77], v[80:81]
	v_pk_mul_f32 v[74:75], v[74:75], v[78:79]
	v_pk_mul_f32 v[78:79], v[58:59], s[18:19] op_sel_hi:[1,0]
	v_pk_mul_f32 v[80:81], v[60:61], s[18:19] op_sel_hi:[1,0]
	v_exp_f32_e32 v82, v82
	v_exp_f32_e32 v83, v83
	v_exp_f32_e32 v84, v84
	v_exp_f32_e32 v85, v85
	v_exp_f32_e32 v78, v78
	v_exp_f32_e32 v79, v79
	v_exp_f32_e32 v80, v80
	v_exp_f32_e32 v81, v81
	v_pk_add_f32 v[82:83], v[82:83], 1.0 op_sel_hi:[1,0]
	v_pk_add_f32 v[84:85], v[84:85], 1.0 op_sel_hi:[1,0]
	v_pk_add_f32 v[78:79], v[78:79], 1.0 op_sel_hi:[1,0]
	v_pk_add_f32 v[80:81], v[80:81], 1.0 op_sel_hi:[1,0]
	v_rcp_f32_e32 v82, v82
	v_rcp_f32_e32 v83, v83
	v_rcp_f32_e32 v84, v84
	v_rcp_f32_e32 v85, v85
	v_rcp_f32_e32 v78, v78
	v_rcp_f32_e32 v79, v79
	v_rcp_f32_e32 v80, v80
	v_rcp_f32_e32 v81, v81
	v_pk_mul_f32 v[60:61], v[60:61], v[68:69]
	v_pk_mul_f32 v[58:59], v[58:59], v[66:67]
	v_pk_mul_f32 v[74:75], v[82:83], v[74:75]
	v_pk_mul_f32 v[76:77], v[84:85], v[76:77]
	v_pk_mul_f32 v[66:67], v[78:79], v[58:59]
	v_pk_mul_f32 v[68:69], v[80:81], v[60:61]
	v_cvt_pk_bf16_f32 v58, v74, v75
	v_cvt_pk_bf16_f32 v59, v76, v77
	v_cvt_pk_bf16_f32 v60, v66, v67
	v_add_u32_e32 v66, 0xb0000, v144
	v_cvt_pk_bf16_f32 v61, v68, v69
	buffer_store_dwordx4 v[58:61], v86, s[4:7], 0 offen sc1
	s_nop 1
	v_pk_mul_f32 v[58:59], v[62:63], s[18:19] op_sel_hi:[1,0]
	v_pk_mul_f32 v[60:61], v[64:65], s[18:19] op_sel_hi:[1,0]
	v_exp_f32_e32 v58, v58
	v_exp_f32_e32 v59, v59
	v_exp_f32_e32 v60, v60
	v_exp_f32_e32 v61, v61
	v_pk_mul_f32 v[64:65], v[64:65], v[72:73]
	v_pk_add_f32 v[58:59], v[58:59], 1.0 op_sel_hi:[1,0]
	v_pk_mul_f32 v[62:63], v[62:63], v[70:71]
	v_pk_add_f32 v[60:61], v[60:61], 1.0 op_sel_hi:[1,0]
	v_rcp_f32_e32 v58, v58
	v_rcp_f32_e32 v59, v59
	v_rcp_f32_e32 v60, v60
	v_rcp_f32_e32 v61, v61
	v_pk_mul_f32 v[58:59], v[58:59], v[62:63]
	v_pk_mul_f32 v[62:63], v[50:51], s[18:19] op_sel_hi:[1,0]
	v_pk_mul_f32 v[60:61], v[60:61], v[64:65]
	v_pk_mul_f32 v[64:65], v[52:53], s[18:19] op_sel_hi:[1,0]
	v_exp_f32_e32 v62, v62
	v_exp_f32_e32 v63, v63
	v_exp_f32_e32 v64, v64
	v_exp_f32_e32 v65, v65
	v_pk_mul_f32 v[52:53], v[52:53], v[56:57]
	v_pk_add_f32 v[62:63], v[62:63], 1.0 op_sel_hi:[1,0]
	v_pk_mul_f32 v[50:51], v[50:51], v[54:55]
	v_pk_add_f32 v[64:65], v[64:65], 1.0 op_sel_hi:[1,0]
	v_rcp_f32_e32 v62, v62
	v_rcp_f32_e32 v63, v63
	v_rcp_f32_e32 v64, v64
	v_rcp_f32_e32 v65, v65
	v_pk_mul_f32 v[54:55], v[62:63], v[50:51]
	v_cvt_pk_bf16_f32 v50, v58, v59
	v_pk_mul_f32 v[56:57], v[64:65], v[52:53]
	v_cvt_pk_bf16_f32 v51, v60, v61
	v_cvt_pk_bf16_f32 v52, v54, v55
	v_add_u32_e32 v54, 0xc6000, v144
	v_cvt_pk_bf16_f32 v53, v56, v57
	buffer_store_dwordx4 v[50:53], v66, s[4:7], 0 offen sc1
	s_nop 1
	v_pk_mul_f32 v[50:51], v[42:43], s[18:19] op_sel_hi:[1,0]
	v_pk_mul_f32 v[52:53], v[44:45], s[18:19] op_sel_hi:[1,0]
	v_pk_mul_f32 v[44:45], v[44:45], v[48:49]
	v_pk_mul_f32 v[42:43], v[42:43], v[46:47]
	v_pk_mul_f32 v[46:47], v[34:35], s[18:19] op_sel_hi:[1,0]
	v_pk_mul_f32 v[48:49], v[36:37], s[18:19] op_sel_hi:[1,0]
	v_exp_f32_e32 v50, v50
	v_exp_f32_e32 v51, v51
	v_exp_f32_e32 v52, v52
	v_exp_f32_e32 v53, v53
	v_exp_f32_e32 v46, v46
	v_exp_f32_e32 v47, v47
	v_exp_f32_e32 v48, v48
	v_exp_f32_e32 v49, v49
	v_pk_add_f32 v[50:51], v[50:51], 1.0 op_sel_hi:[1,0]
	v_pk_add_f32 v[52:53], v[52:53], 1.0 op_sel_hi:[1,0]
	v_pk_add_f32 v[46:47], v[46:47], 1.0 op_sel_hi:[1,0]
	v_pk_add_f32 v[48:49], v[48:49], 1.0 op_sel_hi:[1,0]
	v_rcp_f32_e32 v50, v50
	v_rcp_f32_e32 v51, v51
	v_rcp_f32_e32 v52, v52
	v_rcp_f32_e32 v53, v53
	v_rcp_f32_e32 v46, v46
	v_rcp_f32_e32 v47, v47
	v_rcp_f32_e32 v48, v48
	v_rcp_f32_e32 v49, v49
	v_pk_mul_f32 v[36:37], v[36:37], v[40:41]
	v_pk_mul_f32 v[34:35], v[34:35], v[38:39]
	v_pk_mul_f32 v[42:43], v[50:51], v[42:43]
	v_pk_mul_f32 v[44:45], v[52:53], v[44:45]
	v_pk_mul_f32 v[38:39], v[46:47], v[34:35]
	v_pk_mul_f32 v[40:41], v[48:49], v[36:37]
	v_cvt_pk_bf16_f32 v34, v42, v43
	v_cvt_pk_bf16_f32 v35, v44, v45
	v_cvt_pk_bf16_f32 v36, v38, v39
	v_add_u32_e32 v38, 0xdc000, v144
	v_cvt_pk_bf16_f32 v37, v40, v41
	buffer_store_dwordx4 v[34:37], v54, s[4:7], 0 offen sc1
	s_nop 1
	v_pk_mul_f32 v[34:35], v[26:27], s[18:19] op_sel_hi:[1,0]
	v_pk_mul_f32 v[36:37], v[28:29], s[18:19] op_sel_hi:[1,0]
	v_pk_mul_f32 v[28:29], v[28:29], v[32:33]
	v_pk_mul_f32 v[26:27], v[26:27], v[30:31]
	v_pk_mul_f32 v[30:31], v[18:19], s[18:19] op_sel_hi:[1,0]
	v_pk_mul_f32 v[32:33], v[20:21], s[18:19] op_sel_hi:[1,0]
	v_exp_f32_e32 v34, v34
	v_exp_f32_e32 v35, v35
	v_exp_f32_e32 v36, v36
	v_exp_f32_e32 v37, v37
	v_exp_f32_e32 v30, v30
	v_exp_f32_e32 v31, v31
	v_exp_f32_e32 v32, v32
	v_exp_f32_e32 v33, v33
	v_pk_add_f32 v[34:35], v[34:35], 1.0 op_sel_hi:[1,0]
	v_pk_add_f32 v[36:37], v[36:37], 1.0 op_sel_hi:[1,0]
	v_pk_add_f32 v[30:31], v[30:31], 1.0 op_sel_hi:[1,0]
	v_pk_add_f32 v[32:33], v[32:33], 1.0 op_sel_hi:[1,0]
	v_rcp_f32_e32 v34, v34
	v_rcp_f32_e32 v35, v35
	v_rcp_f32_e32 v36, v36
	v_rcp_f32_e32 v37, v37
	v_rcp_f32_e32 v30, v30
	v_rcp_f32_e32 v31, v31
	v_rcp_f32_e32 v32, v32
	v_rcp_f32_e32 v33, v33
	v_pk_mul_f32 v[20:21], v[20:21], v[24:25]
	v_pk_mul_f32 v[18:19], v[18:19], v[22:23]
	v_pk_mul_f32 v[26:27], v[34:35], v[26:27]
	v_pk_mul_f32 v[28:29], v[36:37], v[28:29]
	v_pk_mul_f32 v[22:23], v[30:31], v[18:19]
	v_pk_mul_f32 v[24:25], v[32:33], v[20:21]
	v_cvt_pk_bf16_f32 v18, v26, v27
	v_cvt_pk_bf16_f32 v19, v28, v29
	v_cvt_pk_bf16_f32 v20, v22, v23
	v_add_u32_e32 v22, 0xf2000, v144
	v_cvt_pk_bf16_f32 v21, v24, v25
	buffer_store_dwordx4 v[18:21], v38, s[4:7], 0 offen sc1
	s_nop 1
	v_pk_mul_f32 v[18:19], v[10:11], s[18:19] op_sel_hi:[1,0]
	v_pk_mul_f32 v[20:21], v[12:13], s[18:19] op_sel_hi:[1,0]
	v_pk_mul_f32 v[12:13], v[12:13], v[16:17]
	v_pk_mul_f32 v[10:11], v[10:11], v[14:15]
	v_pk_mul_f32 v[14:15], v[2:3], s[18:19] op_sel_hi:[1,0]
	v_pk_mul_f32 v[16:17], v[4:5], s[18:19] op_sel_hi:[1,0]
	v_exp_f32_e32 v18, v18
	v_exp_f32_e32 v19, v19
	v_exp_f32_e32 v20, v20
	v_exp_f32_e32 v21, v21
	v_exp_f32_e32 v14, v14
	v_exp_f32_e32 v15, v15
	v_exp_f32_e32 v16, v16
	v_exp_f32_e32 v17, v17
	v_pk_add_f32 v[18:19], v[18:19], 1.0 op_sel_hi:[1,0]
	v_pk_add_f32 v[20:21], v[20:21], 1.0 op_sel_hi:[1,0]
	v_pk_add_f32 v[14:15], v[14:15], 1.0 op_sel_hi:[1,0]
	v_pk_add_f32 v[16:17], v[16:17], 1.0 op_sel_hi:[1,0]
	v_rcp_f32_e32 v18, v18
	v_rcp_f32_e32 v19, v19
	v_rcp_f32_e32 v20, v20
	v_rcp_f32_e32 v21, v21
	v_rcp_f32_e32 v14, v14
	v_rcp_f32_e32 v15, v15
	v_rcp_f32_e32 v16, v16
	v_rcp_f32_e32 v17, v17
	v_pk_mul_f32 v[4:5], v[4:5], v[8:9]
	v_pk_mul_f32 v[2:3], v[2:3], v[6:7]
	v_pk_mul_f32 v[10:11], v[18:19], v[10:11]
	v_pk_mul_f32 v[12:13], v[20:21], v[12:13]
	v_pk_mul_f32 v[6:7], v[14:15], v[2:3]
	v_pk_mul_f32 v[8:9], v[16:17], v[4:5]
	v_cvt_pk_bf16_f32 v2, v10, v11
	v_cvt_pk_bf16_f32 v3, v12, v13
	v_cvt_pk_bf16_f32 v4, v6, v7
	s_nop 0
	v_cvt_pk_bf16_f32 v5, v8, v9
	buffer_store_dwordx4 v[2:5], v22, s[4:7], 0 offen sc1
	s_cbranch_vccnz .LBB0_121
	s_andn2_b64 vcc, exec, s[0:1]
	s_cbranch_vccnz .LBB0_120
	s_barrier
	s_branch .LBB0_120

.LBB0_619:
	ds_read_b128 v[146:149], v141
	ds_read_b128 v[150:153], v141 offset:1024
	ds_read_b128 v[154:157], v141 offset:2048
	ds_read_b128 v[158:161], v141 offset:3072
	ds_read_b128 v[162:165], v142
	ds_read_b128 v[166:169], v142 offset:1024
	ds_read_b128 v[170:173], v142 offset:2048
	ds_read_b128 v[174:177], v142 offset:3072
	s_add_u32 s38, s40, 0x100
	s_addc_u32 s39, s41, 0
	s_cmp_eq_u32 s22, 12
	s_cselect_b32 s48, s76, s38
	s_cselect_b32 s49, s21, s39
	s_cselect_b32 s44, s77, s78
	s_cselect_b32 s45, s19, s85
	s_add_u32 s42, s48, 0x80
	s_addc_u32 s43, s49, 0
	s_add_u32 s24, s40, 0x40080
	s_mov_b32 m0, s80
	s_addc_u32 s25, s41, 0
	v_mov_b32_e32 v210, v134
	ds_read_b128 v[178:181], v143
	ds_read_b128 v[182:185], v143 offset:1024
	ds_read_b128 v[186:189], v143 offset:2048
	ds_read_b128 v[190:193], v143 offset:3072
	ds_read_b128 v[194:197], v143 offset:4096
	ds_read_b128 v[198:201], v143 offset:5120
	ds_read_b128 v[202:205], v143 offset:6144
	ds_read_b128 v[206:209], v143 offset:7168
	v_mov_b32_e32 v211, v136
	global_load_lds_dwordx4 v210, s[24:25]
	s_mov_b32 m0, s81
	s_add_u32 s40, s44, 0x80
	global_load_lds_dwordx4 v211, s[24:25]
	s_waitcnt vmcnt(8)
	s_waitcnt lgkmcnt(0)
	s_addc_u32 s41, s45, 0
	s_barrier
	s_waitcnt lgkmcnt(0)
	v_mfma_f32_16x16x32_bf16 v[122:125], v[146:149], v[178:181], v[122:125]
	v_mfma_f32_16x16x32_bf16 v[114:117], v[154:157], v[178:181], v[114:117]
	v_mfma_f32_16x16x32_bf16 v[106:109], v[146:149], v[186:189], v[106:109]
	v_mfma_f32_16x16x32_bf16 v[98:101], v[154:157], v[186:189], v[98:101]
	v_mfma_f32_16x16x32_bf16 v[90:93], v[146:149], v[194:197], v[90:93]
	v_mfma_f32_16x16x32_bf16 v[82:85], v[154:157], v[194:197], v[82:85]
	v_mfma_f32_16x16x32_bf16 v[74:77], v[146:149], v[202:205], v[74:77]
	v_mfma_f32_16x16x32_bf16 v[54:57], v[154:157], v[202:205], v[54:57]
	v_mfma_f32_16x16x32_bf16 v[122:125], v[150:153], v[182:185], v[122:125]
	v_mfma_f32_16x16x32_bf16 v[114:117], v[158:161], v[182:185], v[114:117]
	v_mfma_f32_16x16x32_bf16 v[106:109], v[150:153], v[190:193], v[106:109]
	v_mfma_f32_16x16x32_bf16 v[98:101], v[158:161], v[190:193], v[98:101]
	v_mfma_f32_16x16x32_bf16 v[90:93], v[150:153], v[198:201], v[90:93]
	v_mfma_f32_16x16x32_bf16 v[82:85], v[158:161], v[198:201], v[82:85]
	v_mfma_f32_16x16x32_bf16 v[74:77], v[150:153], v[206:209], v[74:77]
	v_mfma_f32_16x16x32_bf16 v[54:57], v[158:161], v[206:209], v[54:57]
	v_mfma_f32_16x16x32_bf16 v[126:129], v[162:165], v[178:181], v[126:129]
	v_mfma_f32_16x16x32_bf16 v[118:121], v[170:173], v[178:181], v[118:121]
	v_mfma_f32_16x16x32_bf16 v[110:113], v[162:165], v[186:189], v[110:113]
	v_mfma_f32_16x16x32_bf16 v[102:105], v[170:173], v[186:189], v[102:105]
	v_mfma_f32_16x16x32_bf16 v[94:97], v[162:165], v[194:197], v[94:97]
	v_mfma_f32_16x16x32_bf16 v[86:89], v[170:173], v[194:197], v[86:89]
	v_mfma_f32_16x16x32_bf16 v[78:81], v[162:165], v[202:205], v[78:81]
	v_mfma_f32_16x16x32_bf16 v[62:65], v[170:173], v[202:205], v[62:65]
	v_mfma_f32_16x16x32_bf16 v[126:129], v[166:169], v[182:185], v[126:129]
	v_mfma_f32_16x16x32_bf16 v[118:121], v[174:177], v[182:185], v[118:121]
	v_mfma_f32_16x16x32_bf16 v[110:113], v[166:169], v[190:193], v[110:113]
	v_mfma_f32_16x16x32_bf16 v[102:105], v[174:177], v[190:193], v[102:105]
	v_mfma_f32_16x16x32_bf16 v[94:97], v[166:169], v[198:201], v[94:97]
	v_mfma_f32_16x16x32_bf16 v[86:89], v[174:177], v[198:201], v[86:89]
	v_mfma_f32_16x16x32_bf16 v[78:81], v[166:169], v[206:209], v[78:81]
	v_mfma_f32_16x16x32_bf16 v[62:65], v[174:177], v[206:209], v[62:65]
	s_barrier
	s_mov_b32 m0, s82
	s_mov_b64 s[24:25], s[44:45]
	v_mov_b32_e32 v212, v135
	ds_read_b128 v[178:181], v143 offset:16384
	ds_read_b128 v[182:185], v143 offset:17408
	ds_read_b128 v[186:189], v143 offset:18432
	ds_read_b128 v[190:193], v143 offset:19456
	ds_read_b128 v[194:197], v143 offset:20480
	ds_read_b128 v[198:201], v143 offset:21504
	ds_read_b128 v[202:205], v143 offset:22528
	ds_read_b128 v[206:209], v143 offset:23552
	v_mov_b32_e32 v213, v137
	global_load_lds_dwordx4 v212, s[24:25]
	s_mov_b32 m0, s83
	s_nop 0
	global_load_lds_dwordx4 v213, s[24:25]
	s_add_u32 s24, s44, 0x40000
	s_addc_u32 s25, s45, 0
	s_mov_b32 m0, s34
	s_nop 0
	global_load_lds_dwordx4 v212, s[24:25]
	s_mov_b32 m0, s35
	s_nop 0
	global_load_lds_dwordx4 v213, s[24:25]
	s_mov_b64 s[24:25], s[48:49]
	s_mov_b32 m0, s31
	s_nop 0
	global_load_lds_dwordx4 v210, s[24:25]
	s_mov_b32 m0, s65
	s_nop 0
	global_load_lds_dwordx4 v211, s[24:25]
	s_waitcnt vmcnt(8)
	s_waitcnt lgkmcnt(0)
	s_barrier
	s_waitcnt lgkmcnt(0)
	v_mfma_f32_16x16x32_bf16 v[66:69], v[146:149], v[178:181], v[66:69]
	v_mfma_f32_16x16x32_bf16 v[50:53], v[154:157], v[178:181], v[50:53]
	v_mfma_f32_16x16x32_bf16 v[42:45], v[146:149], v[186:189], v[42:45]
	v_mfma_f32_16x16x32_bf16 v[34:37], v[154:157], v[186:189], v[34:37]
	v_mfma_f32_16x16x32_bf16 v[26:29], v[146:149], v[194:197], v[26:29]
	v_mfma_f32_16x16x32_bf16 v[18:21], v[154:157], v[194:197], v[18:21]
	v_mfma_f32_16x16x32_bf16 v[10:13], v[146:149], v[202:205], v[10:13]
	v_mfma_f32_16x16x32_bf16 v[2:5], v[154:157], v[202:205], v[2:5]
	v_mfma_f32_16x16x32_bf16 v[66:69], v[150:153], v[182:185], v[66:69]
	v_mfma_f32_16x16x32_bf16 v[50:53], v[158:161], v[182:185], v[50:53]
	v_mfma_f32_16x16x32_bf16 v[42:45], v[150:153], v[190:193], v[42:45]
	v_mfma_f32_16x16x32_bf16 v[34:37], v[158:161], v[190:193], v[34:37]
	v_mfma_f32_16x16x32_bf16 v[26:29], v[150:153], v[198:201], v[26:29]
	v_mfma_f32_16x16x32_bf16 v[18:21], v[158:161], v[198:201], v[18:21]
	v_mfma_f32_16x16x32_bf16 v[10:13], v[150:153], v[206:209], v[10:13]
	v_mfma_f32_16x16x32_bf16 v[2:5], v[158:161], v[206:209], v[2:5]
	v_mfma_f32_16x16x32_bf16 v[70:73], v[162:165], v[178:181], v[70:73]
	v_mfma_f32_16x16x32_bf16 v[58:61], v[170:173], v[178:181], v[58:61]
	v_mfma_f32_16x16x32_bf16 v[46:49], v[162:165], v[186:189], v[46:49]
	v_mfma_f32_16x16x32_bf16 v[38:41], v[170:173], v[186:189], v[38:41]
	v_mfma_f32_16x16x32_bf16 v[30:33], v[162:165], v[194:197], v[30:33]
	v_mfma_f32_16x16x32_bf16 v[22:25], v[170:173], v[194:197], v[22:25]
	v_mfma_f32_16x16x32_bf16 v[14:17], v[162:165], v[202:205], v[14:17]
	v_mfma_f32_16x16x32_bf16 v[6:9], v[170:173], v[202:205], v[6:9]
	v_mfma_f32_16x16x32_bf16 v[70:73], v[166:169], v[182:185], v[70:73]
	v_mfma_f32_16x16x32_bf16 v[58:61], v[174:177], v[182:185], v[58:61]
	v_mfma_f32_16x16x32_bf16 v[46:49], v[166:169], v[190:193], v[46:49]
	v_mfma_f32_16x16x32_bf16 v[38:41], v[174:177], v[190:193], v[38:41]
	v_mfma_f32_16x16x32_bf16 v[30:33], v[166:169], v[198:201], v[30:33]
	v_mfma_f32_16x16x32_bf16 v[22:25], v[174:177], v[198:201], v[22:25]
	v_mfma_f32_16x16x32_bf16 v[14:17], v[166:169], v[206:209], v[14:17]
	v_mfma_f32_16x16x32_bf16 v[6:9], v[174:177], v[206:209], v[6:9]
	s_barrier
	ds_read_b128 v[146:149], v144
	ds_read_b128 v[150:153], v144 offset:1024
	ds_read_b128 v[154:157], v144 offset:2048
	ds_read_b128 v[158:161], v144 offset:3072
	ds_read_b128 v[162:165], v145
	ds_read_b128 v[166:169], v145 offset:1024
	ds_read_b128 v[170:173], v145 offset:2048
	ds_read_b128 v[174:177], v145 offset:3072
	s_add_u32 s24, s48, 0x40000
	s_addc_u32 s25, s49, 0
	s_mov_b32 m0, s66
	ds_read_b128 v[178:181], v143 offset:32768
	ds_read_b128 v[182:185], v143 offset:33792
	ds_read_b128 v[186:189], v143 offset:34816
	ds_read_b128 v[190:193], v143 offset:35840
	ds_read_b128 v[194:197], v143 offset:36864
	ds_read_b128 v[198:201], v143 offset:37888
	ds_read_b128 v[202:205], v143 offset:38912
	ds_read_b128 v[206:209], v143 offset:39936
	s_nop 0
	global_load_lds_dwordx4 v210, s[24:25]
	s_mov_b32 m0, s67
	s_nop 0
	global_load_lds_dwordx4 v211, s[24:25]
	s_waitcnt vmcnt(8)
	s_waitcnt lgkmcnt(0)
	s_barrier
	s_waitcnt lgkmcnt(0)
	v_mfma_f32_16x16x32_bf16 v[122:125], v[146:149], v[178:181], v[122:125]
	v_mfma_f32_16x16x32_bf16 v[114:117], v[154:157], v[178:181], v[114:117]
	v_mfma_f32_16x16x32_bf16 v[106:109], v[146:149], v[186:189], v[106:109]
	v_mfma_f32_16x16x32_bf16 v[98:101], v[154:157], v[186:189], v[98:101]
	v_mfma_f32_16x16x32_bf16 v[90:93], v[146:149], v[194:197], v[90:93]
	v_mfma_f32_16x16x32_bf16 v[82:85], v[154:157], v[194:197], v[82:85]
	v_mfma_f32_16x16x32_bf16 v[74:77], v[146:149], v[202:205], v[74:77]
	v_mfma_f32_16x16x32_bf16 v[54:57], v[154:157], v[202:205], v[54:57]
	v_mfma_f32_16x16x32_bf16 v[122:125], v[150:153], v[182:185], v[122:125]
	v_mfma_f32_16x16x32_bf16 v[114:117], v[158:161], v[182:185], v[114:117]
	v_mfma_f32_16x16x32_bf16 v[106:109], v[150:153], v[190:193], v[106:109]
	v_mfma_f32_16x16x32_bf16 v[98:101], v[158:161], v[190:193], v[98:101]
	v_mfma_f32_16x16x32_bf16 v[90:93], v[150:153], v[198:201], v[90:93]
	v_mfma_f32_16x16x32_bf16 v[82:85], v[158:161], v[198:201], v[82:85]
	v_mfma_f32_16x16x32_bf16 v[74:77], v[150:153], v[206:209], v[74:77]
	v_mfma_f32_16x16x32_bf16 v[54:57], v[158:161], v[206:209], v[54:57]
	v_mfma_f32_16x16x32_bf16 v[126:129], v[162:165], v[178:181], v[126:129]
	v_mfma_f32_16x16x32_bf16 v[118:121], v[170:173], v[178:181], v[118:121]
	v_mfma_f32_16x16x32_bf16 v[110:113], v[162:165], v[186:189], v[110:113]
	v_mfma_f32_16x16x32_bf16 v[102:105], v[170:173], v[186:189], v[102:105]
	v_mfma_f32_16x16x32_bf16 v[94:97], v[162:165], v[194:197], v[94:97]
	v_mfma_f32_16x16x32_bf16 v[86:89], v[170:173], v[194:197], v[86:89]
	v_mfma_f32_16x16x32_bf16 v[78:81], v[162:165], v[202:205], v[78:81]
	v_mfma_f32_16x16x32_bf16 v[62:65], v[170:173], v[202:205], v[62:65]
	v_mfma_f32_16x16x32_bf16 v[126:129], v[166:169], v[182:185], v[126:129]
	v_mfma_f32_16x16x32_bf16 v[118:121], v[174:177], v[182:185], v[118:121]
	v_mfma_f32_16x16x32_bf16 v[110:113], v[166:169], v[190:193], v[110:113]
	v_mfma_f32_16x16x32_bf16 v[102:105], v[174:177], v[190:193], v[102:105]
	v_mfma_f32_16x16x32_bf16 v[94:97], v[166:169], v[198:201], v[94:97]
	v_mfma_f32_16x16x32_bf16 v[86:89], v[174:177], v[198:201], v[86:89]
	v_mfma_f32_16x16x32_bf16 v[78:81], v[166:169], v[206:209], v[78:81]
	v_mfma_f32_16x16x32_bf16 v[62:65], v[174:177], v[206:209], v[62:65]
	s_barrier
	s_mov_b32 m0, s11
	ds_read_b128 v[178:181], v143 offset:49152
	ds_read_b128 v[182:185], v143 offset:50176
	ds_read_b128 v[186:189], v143 offset:51200
	ds_read_b128 v[190:193], v143 offset:52224
	ds_read_b128 v[194:197], v143 offset:53248
	ds_read_b128 v[198:201], v143 offset:54272
	ds_read_b128 v[202:205], v143 offset:55296
	ds_read_b128 v[206:209], v143 offset:56320
	s_add_u32 s24, s44, 0x40080
	global_load_lds_dwordx4 v212, s[40:41]
	s_mov_b32 m0, s84
	s_addc_u32 s25, s45, 0
	global_load_lds_dwordx4 v213, s[40:41]
	s_mov_b32 m0, s8
	s_nop 0
	global_load_lds_dwordx4 v212, s[24:25]
	s_mov_b32 m0, s9
	s_nop 0
	global_load_lds_dwordx4 v213, s[24:25]
	s_mov_b32 m0, s69
	s_nop 0
	global_load_lds_dwordx4 v210, s[42:43]
	s_mov_b32 m0, s70
	s_nop 0
	global_load_lds_dwordx4 v211, s[42:43]
	s_waitcnt vmcnt(8)
	s_waitcnt lgkmcnt(0)
	s_barrier
	s_waitcnt lgkmcnt(0)
	v_mfma_f32_16x16x32_bf16 v[66:69], v[146:149], v[178:181], v[66:69]
	v_mfma_f32_16x16x32_bf16 v[50:53], v[154:157], v[178:181], v[50:53]
	v_mfma_f32_16x16x32_bf16 v[42:45], v[146:149], v[186:189], v[42:45]
	v_mfma_f32_16x16x32_bf16 v[34:37], v[154:157], v[186:189], v[34:37]
	v_mfma_f32_16x16x32_bf16 v[26:29], v[146:149], v[194:197], v[26:29]
	v_mfma_f32_16x16x32_bf16 v[18:21], v[154:157], v[194:197], v[18:21]
	v_mfma_f32_16x16x32_bf16 v[10:13], v[146:149], v[202:205], v[10:13]
	v_mfma_f32_16x16x32_bf16 v[2:5], v[154:157], v[202:205], v[2:5]
	v_mfma_f32_16x16x32_bf16 v[66:69], v[150:153], v[182:185], v[66:69]
	v_mfma_f32_16x16x32_bf16 v[50:53], v[158:161], v[182:185], v[50:53]
	v_mfma_f32_16x16x32_bf16 v[42:45], v[150:153], v[190:193], v[42:45]
	v_mfma_f32_16x16x32_bf16 v[34:37], v[158:161], v[190:193], v[34:37]
	v_mfma_f32_16x16x32_bf16 v[26:29], v[150:153], v[198:201], v[26:29]
	v_mfma_f32_16x16x32_bf16 v[18:21], v[158:161], v[198:201], v[18:21]
	v_mfma_f32_16x16x32_bf16 v[10:13], v[150:153], v[206:209], v[10:13]
	v_mfma_f32_16x16x32_bf16 v[2:5], v[158:161], v[206:209], v[2:5]
	v_mfma_f32_16x16x32_bf16 v[70:73], v[162:165], v[178:181], v[70:73]
	v_mfma_f32_16x16x32_bf16 v[58:61], v[170:173], v[178:181], v[58:61]
	v_mfma_f32_16x16x32_bf16 v[46:49], v[162:165], v[186:189], v[46:49]
	v_mfma_f32_16x16x32_bf16 v[38:41], v[170:173], v[186:189], v[38:41]
	v_mfma_f32_16x16x32_bf16 v[30:33], v[162:165], v[194:197], v[30:33]
	v_mfma_f32_16x16x32_bf16 v[22:25], v[170:173], v[194:197], v[22:25]
	v_mfma_f32_16x16x32_bf16 v[14:17], v[162:165], v[202:205], v[14:17]
	v_mfma_f32_16x16x32_bf16 v[6:9], v[170:173], v[202:205], v[6:9]
	v_mfma_f32_16x16x32_bf16 v[70:73], v[166:169], v[182:185], v[70:73]
	v_mfma_f32_16x16x32_bf16 v[58:61], v[174:177], v[182:185], v[58:61]
	v_mfma_f32_16x16x32_bf16 v[46:49], v[166:169], v[190:193], v[46:49]
	v_mfma_f32_16x16x32_bf16 v[38:41], v[174:177], v[190:193], v[38:41]
	v_mfma_f32_16x16x32_bf16 v[30:33], v[166:169], v[198:201], v[30:33]
	v_mfma_f32_16x16x32_bf16 v[22:25], v[174:177], v[198:201], v[22:25]
	v_mfma_f32_16x16x32_bf16 v[14:17], v[166:169], v[206:209], v[14:17]
	v_mfma_f32_16x16x32_bf16 v[6:9], v[174:177], v[206:209], v[6:9]
	s_barrier
	s_add_i32 s22, s22, 2
	s_add_u32 s78, s78, 0x100
	s_addc_u32 s85, s85, 0
	s_cmp_gt_u32 s22, 13
	s_mov_b64 s[40:41], s[38:39]
	s_cbranch_scc0 .LBB0_619
	s_and_b64 vcc, exec, s[12:13]
	s_cbranch_vccz .LBB0_622
	s_nop 0
.LBB0_622:
	v_pk_mul_f32 v[144:145], v[122:123], s[14:15] op_sel_hi:[1,0]
	v_pk_mul_f32 v[122:123], v[122:123], v[126:127]
	v_pk_mul_f32 v[126:127], v[114:115], s[14:15] op_sel_hi:[1,0]
	v_pk_mul_f32 v[146:147], v[124:125], s[14:15] op_sel_hi:[1,0]
	v_exp_f32_e32 v126, v126
	v_exp_f32_e32 v127, v127
	v_pk_mul_f32 v[124:125], v[124:125], v[128:129]
	v_pk_mul_f32 v[128:129], v[116:117], s[14:15] op_sel_hi:[1,0]
	v_pk_mul_f32 v[114:115], v[114:115], v[118:119]
	v_exp_f32_e32 v128, v128
	v_exp_f32_e32 v129, v129
	v_pk_add_f32 v[126:127], v[126:127], 1.0 op_sel_hi:[1,0]
	v_pk_mul_f32 v[116:117], v[116:117], v[120:121]
	v_rcp_f32_e32 v126, v126
	v_rcp_f32_e32 v127, v127
	v_pk_add_f32 v[128:129], v[128:129], 1.0 op_sel_hi:[1,0]
	v_pk_mul_f32 v[120:121], v[106:107], s[14:15] op_sel_hi:[1,0]
	v_rcp_f32_e32 v128, v128
	v_rcp_f32_e32 v129, v129
	v_pk_mul_f32 v[118:119], v[126:127], v[114:115]
	v_mov_b32_e32 v115, 0
	v_cvt_pk_fp8_f32 v115, v118, v119
	v_pk_mul_f32 v[106:107], v[106:107], v[110:111]
	v_pk_mul_f32 v[110:111], v[98:99], s[14:15] op_sel_hi:[1,0]
	v_pk_mul_f32 v[116:117], v[128:129], v[116:117]
	v_exp_f32_e32 v110, v110
	v_exp_f32_e32 v111, v111
	v_cvt_pk_fp8_f32 v115, v116, v117 op_sel:[0,0,1]
	v_pk_mul_f32 v[116:117], v[100:101], s[14:15] op_sel_hi:[1,0]
	v_pk_mul_f32 v[98:99], v[98:99], v[102:103]
	v_pk_add_f32 v[110:111], v[110:111], 1.0 op_sel_hi:[1,0]
	v_exp_f32_e32 v116, v116
	v_exp_f32_e32 v117, v117
	v_rcp_f32_e32 v110, v110
	v_rcp_f32_e32 v111, v111
	v_lshl_add_u32 v148, s30, 8, v139
	v_pk_add_f32 v[102:103], v[116:117], 1.0 op_sel_hi:[1,0]
	v_mov_b32_e32 v117, 0
	v_pk_mul_f32 v[98:99], v[110:111], v[98:99]
	v_rcp_f32_e32 v102, v102
	v_rcp_f32_e32 v103, v103
	v_cvt_pk_fp8_f32 v117, v98, v99
	v_pk_mul_f32 v[98:99], v[100:101], v[104:105]
	s_lshl_b32 s8, s75, 7
	v_pk_mul_f32 v[98:99], v[102:103], v[98:99]
	v_pk_mul_f32 v[100:101], v[92:93], s[14:15] op_sel_hi:[1,0]
	v_cvt_pk_fp8_f32 v117, v98, v99 op_sel:[0,0,1]
	v_mul_lo_u32 v98, v148, s74
	v_add3_u32 v102, v140, s8, v98
	v_pk_mul_f32 v[98:99], v[90:91], s[14:15] op_sel_hi:[1,0]
	v_pk_mul_f32 v[90:91], v[90:91], v[94:95]
	v_pk_mul_f32 v[94:95], v[82:83], s[14:15] op_sel_hi:[1,0]
	v_pk_mul_f32 v[92:93], v[92:93], v[96:97]
	v_exp_f32_e32 v94, v94
	v_exp_f32_e32 v95, v95
	v_pk_mul_f32 v[96:97], v[84:85], s[14:15] op_sel_hi:[1,0]
	v_pk_mul_f32 v[82:83], v[82:83], v[86:87]
	v_exp_f32_e32 v96, v96
	v_exp_f32_e32 v97, v97
	v_pk_add_f32 v[94:95], v[94:95], 1.0 op_sel_hi:[1,0]
	v_pk_mul_f32 v[84:85], v[84:85], v[88:89]
	v_rcp_f32_e32 v94, v94
	v_rcp_f32_e32 v95, v95
	v_pk_add_f32 v[96:97], v[96:97], 1.0 op_sel_hi:[1,0]
	v_pk_mul_f32 v[88:89], v[74:75], s[14:15] op_sel_hi:[1,0]
	v_rcp_f32_e32 v96, v96
	v_rcp_f32_e32 v97, v97
	v_pk_mul_f32 v[86:87], v[94:95], v[82:83]
	v_mov_b32_e32 v83, 0
	v_cvt_pk_fp8_f32 v83, v86, v87
	v_pk_mul_f32 v[74:75], v[74:75], v[78:79]
	v_pk_mul_f32 v[78:79], v[54:55], s[14:15] op_sel_hi:[1,0]
	v_exp_f32_e32 v144, v144
	v_exp_f32_e32 v145, v145
	v_exp_f32_e32 v120, v120
	v_exp_f32_e32 v121, v121
	v_exp_f32_e32 v98, v98
	v_exp_f32_e32 v99, v99
	v_exp_f32_e32 v88, v88
	v_exp_f32_e32 v89, v89
	s_cmp_eq_u64 s[12:13], 0
	s_cbranch_scc1 .Lmy_ab_p9
	s_barrier
.Lmy_ab_p9:
	v_exp_f32_e32 v78, v78
	v_exp_f32_e32 v79, v79
	v_pk_mul_f32 v[84:85], v[96:97], v[84:85]
	v_pk_mul_f32 v[112:113], v[108:109], v[112:113]
	v_pk_mul_f32 v[108:109], v[108:109], s[14:15] op_sel_hi:[1,0]
	v_cvt_pk_fp8_f32 v83, v84, v85 op_sel:[0,0,1]
	v_pk_mul_f32 v[80:81], v[76:77], v[80:81]
	v_pk_mul_f32 v[76:77], v[76:77], s[14:15] op_sel_hi:[1,0]
	v_pk_mul_f32 v[84:85], v[56:57], s[14:15] op_sel_hi:[1,0]
	v_exp_f32_e32 v146, v146
	v_exp_f32_e32 v147, v147
	v_pk_add_f32 v[144:145], v[144:145], 1.0 op_sel_hi:[1,0]
	v_pk_add_f32 v[118:119], v[120:121], 1.0 op_sel_hi:[1,0]
	v_exp_f32_e32 v108, v108
	v_exp_f32_e32 v109, v109
	v_exp_f32_e32 v100, v100
	v_exp_f32_e32 v101, v101
	v_pk_add_f32 v[98:99], v[98:99], 1.0 op_sel_hi:[1,0]
	v_pk_add_f32 v[86:87], v[88:89], 1.0 op_sel_hi:[1,0]
	v_exp_f32_e32 v76, v76
	v_exp_f32_e32 v77, v77
	v_pk_add_f32 v[78:79], v[78:79], 1.0 op_sel_hi:[1,0]
	v_exp_f32_e32 v84, v84
	v_exp_f32_e32 v85, v85
	v_rcp_f32_e32 v144, v144
	v_rcp_f32_e32 v145, v145
	v_rcp_f32_e32 v118, v118
	v_rcp_f32_e32 v119, v119
	v_rcp_f32_e32 v98, v98
	v_rcp_f32_e32 v99, v99
	v_rcp_f32_e32 v86, v86
	v_rcp_f32_e32 v87, v87
	v_rcp_f32_e32 v78, v78
	v_rcp_f32_e32 v79, v79
	v_pk_add_f32 v[146:147], v[146:147], 1.0 op_sel_hi:[1,0]
	v_pk_add_f32 v[108:109], v[108:109], 1.0 op_sel_hi:[1,0]
	v_pk_add_f32 v[100:101], v[100:101], 1.0 op_sel_hi:[1,0]
	v_pk_add_f32 v[76:77], v[76:77], 1.0 op_sel_hi:[1,0]
	v_pk_mul_f32 v[54:55], v[54:55], v[62:63]
	v_pk_add_f32 v[62:63], v[84:85], 1.0 op_sel_hi:[1,0]
	v_rcp_f32_e32 v146, v146
	v_rcp_f32_e32 v147, v147
	v_pk_mul_f32 v[122:123], v[144:145], v[122:123]
	v_mov_b32_e32 v114, 0
	v_pk_mul_f32 v[106:107], v[118:119], v[106:107]
	v_rcp_f32_e32 v108, v108
	v_rcp_f32_e32 v109, v109
	v_mov_b32_e32 v116, 0
	v_rcp_f32_e32 v100, v100
	v_rcp_f32_e32 v101, v101
	v_pk_mul_f32 v[90:91], v[98:99], v[90:91]
	v_mov_b32_e32 v82, 0
	v_pk_mul_f32 v[74:75], v[86:87], v[74:75]
	v_rcp_f32_e32 v76, v76
	v_rcp_f32_e32 v77, v77
	v_pk_mul_f32 v[54:55], v[78:79], v[54:55]
	v_rcp_f32_e32 v62, v62
	v_rcp_f32_e32 v63, v63
	v_mov_b32_e32 v84, 0
	v_mov_b32_e32 v85, 0
	v_cvt_pk_fp8_f32 v114, v122, v123
	v_cvt_pk_fp8_f32 v116, v106, v107
	v_cvt_pk_fp8_f32 v82, v90, v91
	v_cvt_pk_fp8_f32 v84, v74, v75
	v_cvt_pk_fp8_f32 v85, v54, v55
	v_pk_mul_f32 v[54:55], v[56:57], v[64:65]
	v_pk_mul_f32 v[124:125], v[146:147], v[124:125]
	v_pk_mul_f32 v[108:109], v[108:109], v[112:113]
	v_pk_mul_f32 v[92:93], v[100:101], v[92:93]
	v_pk_mul_f32 v[76:77], v[76:77], v[80:81]
	v_pk_mul_f32 v[54:55], v[62:63], v[54:55]
	v_cvt_pk_fp8_f32 v114, v124, v125 op_sel:[0,0,1]
	v_cvt_pk_fp8_f32 v116, v108, v109 op_sel:[0,0,1]
	v_cvt_pk_fp8_f32 v82, v92, v93 op_sel:[0,0,1]
	v_cvt_pk_fp8_f32 v84, v76, v77 op_sel:[0,0,1]
	v_cvt_pk_fp8_f32 v85, v54, v55 op_sel:[0,0,1]
	v_pk_mul_f32 v[56:57], v[68:69], s[14:15] op_sel_hi:[1,0]
	v_permlane16_swap_b32_e32 v114, v116
	v_exp_f32_e32 v56, v56
	v_exp_f32_e32 v57, v57
	v_permlane16_swap_b32_e32 v115, v117
	v_permlane16_swap_b32_e32 v82, v84
	v_permlane16_swap_b32_e32 v83, v85
	v_add_u32_e32 v54, 0x16000, v102
	buffer_store_dwordx4 v[114:117], v102, s[4:7], 0 offen sc1
	buffer_store_dwordx4 v[82:85], v54, s[4:7], 0 offen sc1
	v_pk_mul_f32 v[54:55], v[66:67], s[14:15] op_sel_hi:[1,0]
	v_pk_add_f32 v[56:57], v[56:57], 1.0 op_sel_hi:[1,0]
	v_exp_f32_e32 v54, v54
	v_exp_f32_e32 v55, v55
	v_rcp_f32_e32 v56, v56
	v_rcp_f32_e32 v57, v57
	v_pk_mul_f32 v[62:63], v[68:69], v[72:73]
	v_pk_add_f32 v[54:55], v[54:55], 1.0 op_sel_hi:[1,0]
	v_pk_mul_f32 v[64:65], v[66:67], v[70:71]
	v_rcp_f32_e32 v54, v54
	v_rcp_f32_e32 v55, v55
	v_pk_mul_f32 v[56:57], v[56:57], v[62:63]
	v_pk_mul_f32 v[62:63], v[50:51], s[14:15] op_sel_hi:[1,0]
	v_pk_mul_f32 v[50:51], v[50:51], v[58:59]
	v_exp_f32_e32 v62, v62
	v_exp_f32_e32 v63, v63
	v_pk_mul_f32 v[54:55], v[54:55], v[64:65]
	v_pk_mul_f32 v[64:65], v[52:53], s[14:15] op_sel_hi:[1,0]
	v_pk_mul_f32 v[52:53], v[52:53], v[60:61]
	v_exp_f32_e32 v64, v64
	v_exp_f32_e32 v65, v65
	v_pk_add_f32 v[62:63], v[62:63], 1.0 op_sel_hi:[1,0]
	v_pk_mul_f32 v[48:49], v[44:45], v[48:49]
	v_rcp_f32_e32 v62, v62
	v_rcp_f32_e32 v63, v63
	v_pk_add_f32 v[64:65], v[64:65], 1.0 op_sel_hi:[1,0]
	v_pk_mul_f32 v[44:45], v[44:45], s[14:15] op_sel_hi:[1,0]
	v_rcp_f32_e32 v64, v64
	v_rcp_f32_e32 v65, v65
	v_pk_mul_f32 v[58:59], v[62:63], v[50:51]
	v_mov_b32_e32 v50, 0
	v_mov_b32_e32 v51, 0
	v_cvt_pk_fp8_f32 v50, v54, v55
	v_pk_mul_f32 v[54:55], v[42:43], s[14:15] op_sel_hi:[1,0]
	v_cvt_pk_fp8_f32 v51, v58, v59
	v_pk_mul_f32 v[42:43], v[42:43], v[46:47]
	v_pk_mul_f32 v[46:47], v[34:35], s[14:15] op_sel_hi:[1,0]
	v_exp_f32_e32 v54, v54
	v_exp_f32_e32 v55, v55
	v_exp_f32_e32 v46, v46
	v_exp_f32_e32 v47, v47
	v_pk_mul_f32 v[52:53], v[64:65], v[52:53]
	v_pk_add_f32 v[54:55], v[54:55], 1.0 op_sel_hi:[1,0]
	v_cvt_pk_fp8_f32 v51, v52, v53 op_sel:[0,0,1]
	v_pk_mul_f32 v[52:53], v[36:37], s[14:15] op_sel_hi:[1,0]
	v_exp_f32_e32 v44, v44
	v_exp_f32_e32 v45, v45
	v_pk_add_f32 v[46:47], v[46:47], 1.0 op_sel_hi:[1,0]
	v_exp_f32_e32 v52, v52
	v_exp_f32_e32 v53, v53
	v_rcp_f32_e32 v54, v54
	v_rcp_f32_e32 v55, v55
	v_rcp_f32_e32 v46, v46
	v_rcp_f32_e32 v47, v47
	v_pk_add_f32 v[44:45], v[44:45], 1.0 op_sel_hi:[1,0]
	v_pk_mul_f32 v[34:35], v[34:35], v[38:39]
	v_pk_add_f32 v[38:39], v[52:53], 1.0 op_sel_hi:[1,0]
	v_pk_mul_f32 v[42:43], v[54:55], v[42:43]
	v_rcp_f32_e32 v44, v44
	v_rcp_f32_e32 v45, v45
	v_pk_mul_f32 v[34:35], v[46:47], v[34:35]
	v_rcp_f32_e32 v38, v38
	v_rcp_f32_e32 v39, v39
	v_mov_b32_e32 v52, 0
	v_mov_b32_e32 v53, 0
	v_cvt_pk_fp8_f32 v52, v42, v43
	v_cvt_pk_fp8_f32 v53, v34, v35
	v_pk_mul_f32 v[34:35], v[36:37], v[40:41]
	v_pk_mul_f32 v[44:45], v[44:45], v[48:49]
	v_pk_mul_f32 v[34:35], v[38:39], v[34:35]
	v_cvt_pk_fp8_f32 v50, v56, v57 op_sel:[0,0,1]
	v_cvt_pk_fp8_f32 v52, v44, v45 op_sel:[0,0,1]
	v_cvt_pk_fp8_f32 v53, v34, v35 op_sel:[0,0,1]
	v_add_u32_e32 v34, 0x58000, v102
	v_pk_mul_f32 v[36:37], v[28:29], s[14:15] op_sel_hi:[1,0]
	v_permlane16_swap_b32_e32 v50, v52
	v_permlane16_swap_b32_e32 v51, v53
	buffer_store_dwordx4 v[50:53], v34, s[4:7], 0 offen sc1
	v_pk_mul_f32 v[34:35], v[26:27], s[14:15] op_sel_hi:[1,0]
	v_pk_mul_f32 v[26:27], v[26:27], v[30:31]
	v_pk_mul_f32 v[30:31], v[18:19], s[14:15] op_sel_hi:[1,0]
	v_pk_mul_f32 v[28:29], v[28:29], v[32:33]
	v_exp_f32_e32 v30, v30
	v_exp_f32_e32 v31, v31
	v_pk_mul_f32 v[32:33], v[20:21], s[14:15] op_sel_hi:[1,0]
	v_pk_mul_f32 v[18:19], v[18:19], v[22:23]
	v_exp_f32_e32 v32, v32
	v_exp_f32_e32 v33, v33
	v_pk_add_f32 v[30:31], v[30:31], 1.0 op_sel_hi:[1,0]
	v_pk_mul_f32 v[20:21], v[20:21], v[24:25]
	v_rcp_f32_e32 v30, v30
	v_rcp_f32_e32 v31, v31
	v_pk_add_f32 v[32:33], v[32:33], 1.0 op_sel_hi:[1,0]
	v_pk_mul_f32 v[24:25], v[10:11], s[14:15] op_sel_hi:[1,0]
	v_rcp_f32_e32 v32, v32
	v_rcp_f32_e32 v33, v33
	v_pk_mul_f32 v[22:23], v[30:31], v[18:19]
	v_mov_b32_e32 v19, 0
	v_cvt_pk_fp8_f32 v19, v22, v23
	v_pk_mul_f32 v[10:11], v[10:11], v[14:15]
	v_pk_mul_f32 v[14:15], v[2:3], s[14:15] op_sel_hi:[1,0]
	v_exp_f32_e32 v34, v34
	v_exp_f32_e32 v35, v35
	v_exp_f32_e32 v24, v24
	v_exp_f32_e32 v25, v25
	v_exp_f32_e32 v14, v14
	v_exp_f32_e32 v15, v15
	v_pk_mul_f32 v[20:21], v[32:33], v[20:21]
	v_pk_mul_f32 v[16:17], v[12:13], v[16:17]
	v_cvt_pk_fp8_f32 v19, v20, v21 op_sel:[0,0,1]
	v_pk_mul_f32 v[12:13], v[12:13], s[14:15] op_sel_hi:[1,0]
	v_pk_mul_f32 v[20:21], v[4:5], s[14:15] op_sel_hi:[1,0]
	v_exp_f32_e32 v36, v36
	v_exp_f32_e32 v37, v37
	v_pk_add_f32 v[34:35], v[34:35], 1.0 op_sel_hi:[1,0]
	v_pk_add_f32 v[22:23], v[24:25], 1.0 op_sel_hi:[1,0]
	v_exp_f32_e32 v12, v12
	v_exp_f32_e32 v13, v13
	v_pk_add_f32 v[14:15], v[14:15], 1.0 op_sel_hi:[1,0]
	v_exp_f32_e32 v20, v20
	v_exp_f32_e32 v21, v21
	v_rcp_f32_e32 v34, v34
	v_rcp_f32_e32 v35, v35
	v_rcp_f32_e32 v22, v22
	v_rcp_f32_e32 v23, v23
	v_rcp_f32_e32 v14, v14
	v_rcp_f32_e32 v15, v15
	v_pk_add_f32 v[36:37], v[36:37], 1.0 op_sel_hi:[1,0]
	v_pk_add_f32 v[12:13], v[12:13], 1.0 op_sel_hi:[1,0]
	v_pk_mul_f32 v[2:3], v[2:3], v[6:7]
	v_pk_add_f32 v[6:7], v[20:21], 1.0 op_sel_hi:[1,0]
	v_rcp_f32_e32 v36, v36
	v_rcp_f32_e32 v37, v37
	v_pk_mul_f32 v[26:27], v[34:35], v[26:27]
	v_mov_b32_e32 v18, 0
	v_pk_mul_f32 v[10:11], v[22:23], v[10:11]
	v_rcp_f32_e32 v12, v12
	v_rcp_f32_e32 v13, v13
	v_pk_mul_f32 v[2:3], v[14:15], v[2:3]
	v_rcp_f32_e32 v6, v6
	v_rcp_f32_e32 v7, v7
	v_mov_b32_e32 v20, 0
	v_mov_b32_e32 v21, 0
	v_cvt_pk_fp8_f32 v18, v26, v27
	v_cvt_pk_fp8_f32 v20, v10, v11
	v_cvt_pk_fp8_f32 v21, v2, v3
	v_pk_mul_f32 v[2:3], v[4:5], v[8:9]
	v_pk_mul_f32 v[28:29], v[36:37], v[28:29]
	v_pk_mul_f32 v[12:13], v[12:13], v[16:17]
	v_pk_mul_f32 v[2:3], v[6:7], v[2:3]
	v_cvt_pk_fp8_f32 v18, v28, v29 op_sel:[0,0,1]
	v_cvt_pk_fp8_f32 v20, v12, v13 op_sel:[0,0,1]
	v_cvt_pk_fp8_f32 v21, v2, v3 op_sel:[0,0,1]
	v_add_u32_e32 v2, 0x6e000, v102
	s_andn2_b64 vcc, exec, s[2:3]
	v_permlane16_swap_b32_e32 v18, v20
	v_permlane16_swap_b32_e32 v19, v21
	s_mov_b64 s[2:3], -1
	buffer_store_dwordx4 v[18:21], v2, s[4:7], 0 offen sc1
	s_cbranch_vccnz .LBB0_615
	s_andn2_b64 vcc, exec, s[0:1]
	s_cbranch_vccnz .LBB0_614
	s_barrier
	s_branch .LBB0_614
